# baseline (speedup 1.0000x reference)
.LBB0_254:
	v_add_u32_e32 v188, v239, v238
	ds_read_b128 v[132:135], v188
	ds_read_b128 v[136:139], v188 offset:1024
	ds_read_b128 v[140:143], v188 offset:2048
	ds_read_b128 v[144:147], v188 offset:3072
	s_add_i32 s71, s58, s70
	v_readfirstlane_b32 s47, v241
	s_add_i32 s46, s71, 0xffffff80
	s_mov_b32 m0, s47
	s_add_i32 vcc_lo, s85, s70
	v_readfirstlane_b32 s47, v240
	ds_read_b128 v[148:151], v237
	ds_read_b128 v[152:155], v237 offset:1024
	ds_read_b128 v[156:159], v237 offset:2048
	ds_read_b128 v[160:163], v237 offset:3072
	ds_read_b128 v[164:167], v237 offset:4096
	ds_read_b128 v[168:171], v237 offset:5120
	ds_read_b128 v[172:175], v237 offset:6144
	ds_read_b128 v[176:179], v237 offset:7168
	buffer_load_dwordx4 v0, s[24:27], s46 offen lds
	s_add_i32 s46, vcc_lo, 0xffffff80
	s_mov_b32 m0, s47
	s_nop 0
	buffer_load_dwordx4 v0, s[24:27], s46 offen lds
	s_waitcnt lgkmcnt(8)
	s_barrier
	s_waitcnt lgkmcnt(0)
	s_waitcnt lgkmcnt(7)
	v_mfma_f32_16x16x32_bf16 v[126:129], v[132:135], v[148:151], v[126:129]
	v_mfma_f32_16x16x32_bf16 v[122:125], v[140:143], v[148:151], v[122:125]
	s_waitcnt lgkmcnt(5)
	v_mfma_f32_16x16x32_bf16 v[118:121], v[132:135], v[156:159], v[118:121]
	v_mfma_f32_16x16x32_bf16 v[114:117], v[140:143], v[156:159], v[114:117]
	s_waitcnt lgkmcnt(3)
	v_mfma_f32_16x16x32_bf16 v[110:113], v[132:135], v[164:167], v[110:113]
	v_mfma_f32_16x16x32_bf16 v[106:109], v[140:143], v[164:167], v[106:109]
	s_waitcnt lgkmcnt(1)
	v_mfma_f32_16x16x32_bf16 v[102:105], v[132:135], v[172:175], v[102:105]
	v_mfma_f32_16x16x32_bf16 v[98:101], v[140:143], v[172:175], v[98:101]
	v_mfma_f32_16x16x32_bf16 v[126:129], v[136:139], v[152:155], v[126:129]
	v_mfma_f32_16x16x32_bf16 v[122:125], v[144:147], v[152:155], v[122:125]
	v_mfma_f32_16x16x32_bf16 v[118:121], v[136:139], v[160:163], v[118:121]
	v_mfma_f32_16x16x32_bf16 v[114:117], v[144:147], v[160:163], v[114:117]
	v_mfma_f32_16x16x32_bf16 v[110:113], v[136:139], v[168:171], v[110:113]
	v_mfma_f32_16x16x32_bf16 v[106:109], v[144:147], v[168:171], v[106:109]
	s_waitcnt lgkmcnt(0)
	v_mfma_f32_16x16x32_bf16 v[102:105], v[136:139], v[176:179], v[102:105]
	v_mfma_f32_16x16x32_bf16 v[98:101], v[144:147], v[176:179], v[98:101]
	s_barrier
	v_readfirstlane_b32 s50, v236
	s_mov_b32 s46, s26
	s_mov_b32 s47, s27
	s_mov_b32 m0, s50
	v_readfirstlane_b32 s55, v235
	ds_read_b128 v[180:183], v188 offset:16384
	ds_read_b128 v[184:187], v188 offset:17408
	ds_read_b128 v[198:201], v188 offset:18432
	ds_read_b128 v[248:251], v188 offset:19456
	buffer_load_dwordx4 v0, s[44:47], s70 offen lds
	s_add_i32 s50, s8, s70
	s_mov_b32 m0, s55
	s_add_i32 s2, s2, 2
	buffer_load_dwordx4 v0, s[44:47], s50 offen lds
	s_barrier
	s_waitcnt lgkmcnt(0)
	s_waitcnt lgkmcnt(3)
	v_mfma_f32_16x16x32_bf16 v[94:97], v[180:183], v[148:151], v[94:97]
	s_waitcnt lgkmcnt(1)
	v_mfma_f32_16x16x32_bf16 v[90:93], v[198:201], v[148:151], v[90:93]
	v_mfma_f32_16x16x32_bf16 v[86:89], v[180:183], v[156:159], v[86:89]
	v_mfma_f32_16x16x32_bf16 v[82:85], v[198:201], v[156:159], v[82:85]
	v_mfma_f32_16x16x32_bf16 v[78:81], v[180:183], v[164:167], v[78:81]
	v_mfma_f32_16x16x32_bf16 v[74:77], v[198:201], v[164:167], v[74:77]
	v_mfma_f32_16x16x32_bf16 v[70:73], v[180:183], v[172:175], v[70:73]
	v_mfma_f32_16x16x32_bf16 v[66:69], v[198:201], v[172:175], v[66:69]
	v_mfma_f32_16x16x32_bf16 v[94:97], v[184:187], v[152:155], v[94:97]
	s_waitcnt lgkmcnt(0)
	v_mfma_f32_16x16x32_bf16 v[90:93], v[248:251], v[152:155], v[90:93]
	v_mfma_f32_16x16x32_bf16 v[86:89], v[184:187], v[160:163], v[86:89]
	v_mfma_f32_16x16x32_bf16 v[82:85], v[248:251], v[160:163], v[82:85]
	v_mfma_f32_16x16x32_bf16 v[78:81], v[184:187], v[168:171], v[78:81]
	v_mfma_f32_16x16x32_bf16 v[74:77], v[248:251], v[168:171], v[74:77]
	v_mfma_f32_16x16x32_bf16 v[70:73], v[184:187], v[176:179], v[70:73]
	v_mfma_f32_16x16x32_bf16 v[66:69], v[248:251], v[176:179], v[66:69]
	v_readfirstlane_b32 s55, v232
	s_mov_b32 m0, s55
	v_readfirstlane_b32 s55, v234
	s_barrier
	ds_read_b128 v[148:151], v237 offset:16384
	ds_read_b128 v[152:155], v237 offset:17408
	ds_read_b128 v[156:159], v237 offset:18432
	ds_read_b128 v[160:163], v237 offset:19456
	ds_read_b128 v[164:167], v237 offset:20480
	ds_read_b128 v[168:171], v237 offset:21504
	ds_read_b128 v[172:175], v237 offset:22528
	ds_read_b128 v[176:179], v237 offset:23552
	buffer_load_dwordx4 v0, s[24:27], s70 offen lds
	s_mov_b32 m0, s55
	s_nop 0
	buffer_load_dwordx4 v0, s[24:27], s50 offen lds
	s_barrier
	s_waitcnt lgkmcnt(0)
	s_waitcnt lgkmcnt(7)
	v_mfma_f32_16x16x32_bf16 v[62:65], v[132:135], v[148:151], v[62:65]
	v_mfma_f32_16x16x32_bf16 v[58:61], v[140:143], v[148:151], v[58:61]
	s_waitcnt lgkmcnt(5)
	v_mfma_f32_16x16x32_bf16 v[54:57], v[132:135], v[156:159], v[54:57]
	v_mfma_f32_16x16x32_bf16 v[50:53], v[140:143], v[156:159], v[50:53]
	s_waitcnt lgkmcnt(3)
	v_mfma_f32_16x16x32_bf16 v[46:49], v[132:135], v[164:167], v[46:49]
	v_mfma_f32_16x16x32_bf16 v[42:45], v[140:143], v[164:167], v[42:45]
	s_waitcnt lgkmcnt(1)
	v_mfma_f32_16x16x32_bf16 v[38:41], v[132:135], v[172:175], v[38:41]
	v_mfma_f32_16x16x32_bf16 v[34:37], v[140:143], v[172:175], v[34:37]
	v_mfma_f32_16x16x32_bf16 v[62:65], v[136:139], v[152:155], v[62:65]
	v_mfma_f32_16x16x32_bf16 v[58:61], v[144:147], v[152:155], v[58:61]
	v_mfma_f32_16x16x32_bf16 v[54:57], v[136:139], v[160:163], v[54:57]
	v_mfma_f32_16x16x32_bf16 v[50:53], v[144:147], v[160:163], v[50:53]
	v_mfma_f32_16x16x32_bf16 v[46:49], v[136:139], v[168:171], v[46:49]
	v_mfma_f32_16x16x32_bf16 v[42:45], v[144:147], v[168:171], v[42:45]
	s_waitcnt lgkmcnt(0)
	v_mfma_f32_16x16x32_bf16 v[38:41], v[136:139], v[176:179], v[38:41]
	v_mfma_f32_16x16x32_bf16 v[34:37], v[144:147], v[176:179], v[34:37]
	s_barrier
	v_readfirstlane_b32 s55, v233
	s_mov_b32 m0, s55
	v_readfirstlane_b32 s55, v231
	buffer_load_dwordx4 v0, s[44:47], s71 offen lds
	s_mov_b32 m0, s55
	s_nop 0
	buffer_load_dwordx4 v0, s[44:47], vcc_lo offen lds
	s_waitcnt vmcnt(6)
	s_barrier
	v_mfma_f32_16x16x32_bf16 v[30:33], v[180:183], v[148:151], v[30:33]
	v_mfma_f32_16x16x32_bf16 v[26:29], v[198:201], v[148:151], v[26:29]
	v_mfma_f32_16x16x32_bf16 v[22:25], v[180:183], v[156:159], v[22:25]
	v_mfma_f32_16x16x32_bf16 v[18:21], v[198:201], v[156:159], v[18:21]
	v_mfma_f32_16x16x32_bf16 v[14:17], v[180:183], v[164:167], v[14:17]
	v_mfma_f32_16x16x32_bf16 v[10:13], v[198:201], v[164:167], v[10:13]
	v_mfma_f32_16x16x32_bf16 v[6:9], v[180:183], v[172:175], v[6:9]
	v_mfma_f32_16x16x32_bf16 v[2:5], v[198:201], v[172:175], v[2:5]
	v_mfma_f32_16x16x32_bf16 v[30:33], v[184:187], v[152:155], v[30:33]
	v_mfma_f32_16x16x32_bf16 v[26:29], v[248:251], v[152:155], v[26:29]
	v_mfma_f32_16x16x32_bf16 v[22:25], v[184:187], v[160:163], v[22:25]
	v_mfma_f32_16x16x32_bf16 v[18:21], v[248:251], v[160:163], v[18:21]
	v_mfma_f32_16x16x32_bf16 v[14:17], v[184:187], v[168:171], v[14:17]
	v_mfma_f32_16x16x32_bf16 v[10:13], v[248:251], v[168:171], v[10:13]
	v_mfma_f32_16x16x32_bf16 v[6:9], v[184:187], v[176:179], v[6:9]
	v_mfma_f32_16x16x32_bf16 v[2:5], v[248:251], v[176:179], v[2:5]
	s_barrier
	ds_read_b128 v[132:135], v188 offset:32768
	ds_read_b128 v[136:139], v188 offset:33792
	ds_read_b128 v[140:143], v188 offset:34816
	ds_read_b128 v[144:147], v188 offset:35840
	v_readfirstlane_b32 s55, v230
	s_mov_b32 m0, s55
	v_readfirstlane_b32 s55, v205
	ds_read_b128 v[148:151], v237 offset:32768
	ds_read_b128 v[152:155], v237 offset:33792
	ds_read_b128 v[156:159], v237 offset:34816
	ds_read_b128 v[160:163], v237 offset:35840
	ds_read_b128 v[164:167], v237 offset:36864
	ds_read_b128 v[168:171], v237 offset:37888
	ds_read_b128 v[172:175], v237 offset:38912
	ds_read_b128 v[176:179], v237 offset:39936
	buffer_load_dwordx4 v0, s[24:27], s71 offen lds
	s_mov_b32 m0, s55
	s_nop 0
	buffer_load_dwordx4 v0, s[24:27], vcc_lo offen lds
	s_waitcnt lgkmcnt(8)
	s_barrier
	s_waitcnt lgkmcnt(0)
	s_waitcnt lgkmcnt(7)
	v_mfma_f32_16x16x32_bf16 v[126:129], v[132:135], v[148:151], v[126:129]
	v_mfma_f32_16x16x32_bf16 v[122:125], v[140:143], v[148:151], v[122:125]
	s_waitcnt lgkmcnt(5)
	v_mfma_f32_16x16x32_bf16 v[118:121], v[132:135], v[156:159], v[118:121]
	v_mfma_f32_16x16x32_bf16 v[114:117], v[140:143], v[156:159], v[114:117]
	s_waitcnt lgkmcnt(3)
	v_mfma_f32_16x16x32_bf16 v[110:113], v[132:135], v[164:167], v[110:113]
	v_mfma_f32_16x16x32_bf16 v[106:109], v[140:143], v[164:167], v[106:109]
	s_waitcnt lgkmcnt(1)
	v_mfma_f32_16x16x32_bf16 v[102:105], v[132:135], v[172:175], v[102:105]
	v_mfma_f32_16x16x32_bf16 v[98:101], v[140:143], v[172:175], v[98:101]
	v_mfma_f32_16x16x32_bf16 v[126:129], v[136:139], v[152:155], v[126:129]
	v_mfma_f32_16x16x32_bf16 v[122:125], v[144:147], v[152:155], v[122:125]
	v_mfma_f32_16x16x32_bf16 v[118:121], v[136:139], v[160:163], v[118:121]
	v_mfma_f32_16x16x32_bf16 v[114:117], v[144:147], v[160:163], v[114:117]
	v_mfma_f32_16x16x32_bf16 v[110:113], v[136:139], v[168:171], v[110:113]
	v_mfma_f32_16x16x32_bf16 v[106:109], v[144:147], v[168:171], v[106:109]
	s_waitcnt lgkmcnt(0)
	v_mfma_f32_16x16x32_bf16 v[102:105], v[136:139], v[176:179], v[102:105]
	v_mfma_f32_16x16x32_bf16 v[98:101], v[144:147], v[176:179], v[98:101]
	s_barrier
	v_readfirstlane_b32 s87, v242
	s_add_i32 s55, s70, 0x80
	s_mov_b32 m0, s87
	v_readfirstlane_b32 s87, v243
	ds_read_b128 v[180:183], v188 offset:49152
	ds_read_b128 v[184:187], v188 offset:50176
	ds_read_b128 v[198:201], v188 offset:51200
	ds_read_b128 v[248:251], v188 offset:52224
	buffer_load_dwordx4 v0, s[44:47], s55 offen lds
	s_addk_i32 s50, 0x80
	s_mov_b32 m0, s87
	s_nop 0
	buffer_load_dwordx4 v0, s[44:47], s50 offen lds
	s_barrier
	s_waitcnt lgkmcnt(0)
	s_waitcnt lgkmcnt(3)
	v_mfma_f32_16x16x32_bf16 v[94:97], v[180:183], v[148:151], v[94:97]
	s_waitcnt lgkmcnt(1)
	v_mfma_f32_16x16x32_bf16 v[90:93], v[198:201], v[148:151], v[90:93]
	v_mfma_f32_16x16x32_bf16 v[86:89], v[180:183], v[156:159], v[86:89]
	v_mfma_f32_16x16x32_bf16 v[82:85], v[198:201], v[156:159], v[82:85]
	v_mfma_f32_16x16x32_bf16 v[78:81], v[180:183], v[164:167], v[78:81]
	v_mfma_f32_16x16x32_bf16 v[74:77], v[198:201], v[164:167], v[74:77]
	v_mfma_f32_16x16x32_bf16 v[70:73], v[180:183], v[172:175], v[70:73]
	v_mfma_f32_16x16x32_bf16 v[66:69], v[198:201], v[172:175], v[66:69]
	v_mfma_f32_16x16x32_bf16 v[94:97], v[184:187], v[152:155], v[94:97]
	s_waitcnt lgkmcnt(0)
	v_mfma_f32_16x16x32_bf16 v[90:93], v[248:251], v[152:155], v[90:93]
	v_mfma_f32_16x16x32_bf16 v[86:89], v[184:187], v[160:163], v[86:89]
	v_mfma_f32_16x16x32_bf16 v[82:85], v[248:251], v[160:163], v[82:85]
	v_mfma_f32_16x16x32_bf16 v[78:81], v[184:187], v[168:171], v[78:81]
	v_mfma_f32_16x16x32_bf16 v[74:77], v[248:251], v[168:171], v[74:77]
	v_mfma_f32_16x16x32_bf16 v[70:73], v[184:187], v[176:179], v[70:73]
	v_mfma_f32_16x16x32_bf16 v[66:69], v[248:251], v[176:179], v[66:69]
	v_readfirstlane_b32 s87, v244
	s_mov_b32 m0, s87
	s_barrier
	ds_read_b128 v[148:151], v237 offset:49152
	ds_read_b128 v[152:155], v237 offset:50176
	ds_read_b128 v[156:159], v237 offset:51200
	ds_read_b128 v[160:163], v237 offset:52224
	ds_read_b128 v[164:167], v237 offset:53248
	ds_read_b128 v[168:171], v237 offset:54272
	ds_read_b128 v[172:175], v237 offset:55296
	ds_read_b128 v[176:179], v237 offset:56320
	buffer_load_dwordx4 v0, s[24:27], s55 offen lds
	v_readfirstlane_b32 s55, v245
	s_mov_b32 m0, s55
	s_nop 0
	buffer_load_dwordx4 v0, s[24:27], s50 offen lds
	s_barrier
	s_waitcnt lgkmcnt(0)
	s_waitcnt lgkmcnt(7)
	v_mfma_f32_16x16x32_bf16 v[62:65], v[132:135], v[148:151], v[62:65]
	v_mfma_f32_16x16x32_bf16 v[58:61], v[140:143], v[148:151], v[58:61]
	s_waitcnt lgkmcnt(5)
	v_mfma_f32_16x16x32_bf16 v[54:57], v[132:135], v[156:159], v[54:57]
	v_mfma_f32_16x16x32_bf16 v[50:53], v[140:143], v[156:159], v[50:53]
	s_waitcnt lgkmcnt(3)
	v_mfma_f32_16x16x32_bf16 v[46:49], v[132:135], v[164:167], v[46:49]
	v_mfma_f32_16x16x32_bf16 v[42:45], v[140:143], v[164:167], v[42:45]
	s_waitcnt lgkmcnt(1)
	v_mfma_f32_16x16x32_bf16 v[38:41], v[132:135], v[172:175], v[38:41]
	v_mfma_f32_16x16x32_bf16 v[34:37], v[140:143], v[172:175], v[34:37]
	v_mfma_f32_16x16x32_bf16 v[62:65], v[136:139], v[152:155], v[62:65]
	v_mfma_f32_16x16x32_bf16 v[58:61], v[144:147], v[152:155], v[58:61]
	v_mfma_f32_16x16x32_bf16 v[54:57], v[136:139], v[160:163], v[54:57]
	v_mfma_f32_16x16x32_bf16 v[50:53], v[144:147], v[160:163], v[50:53]
	v_mfma_f32_16x16x32_bf16 v[46:49], v[136:139], v[168:171], v[46:49]
	v_mfma_f32_16x16x32_bf16 v[42:45], v[144:147], v[168:171], v[42:45]
	s_waitcnt lgkmcnt(0)
	v_mfma_f32_16x16x32_bf16 v[38:41], v[136:139], v[176:179], v[38:41]
	v_mfma_f32_16x16x32_bf16 v[34:37], v[144:147], v[176:179], v[34:37]
	s_barrier
	v_readfirstlane_b32 s50, v246
	s_addk_i32 s71, 0x80
	s_mov_b32 m0, s50
	v_readfirstlane_b32 s50, v247
	buffer_load_dwordx4 v0, s[44:47], s71 offen lds
	s_addk_i32 vcc_lo, 0x80
	s_mov_b32 m0, s50
	s_nop 0
	buffer_load_dwordx4 v0, s[44:47], vcc_lo offen lds
	s_waitcnt vmcnt(6)
	s_barrier
	v_mfma_f32_16x16x32_bf16 v[30:33], v[180:183], v[148:151], v[30:33]
	v_mfma_f32_16x16x32_bf16 v[26:29], v[198:201], v[148:151], v[26:29]
	v_mfma_f32_16x16x32_bf16 v[22:25], v[180:183], v[156:159], v[22:25]
	v_mfma_f32_16x16x32_bf16 v[18:21], v[198:201], v[156:159], v[18:21]
	v_mfma_f32_16x16x32_bf16 v[14:17], v[180:183], v[164:167], v[14:17]
	v_mfma_f32_16x16x32_bf16 v[10:13], v[198:201], v[164:167], v[10:13]
	v_mfma_f32_16x16x32_bf16 v[6:9], v[180:183], v[172:175], v[6:9]
	v_mfma_f32_16x16x32_bf16 v[2:5], v[198:201], v[172:175], v[2:5]
	v_mfma_f32_16x16x32_bf16 v[30:33], v[184:187], v[152:155], v[30:33]
	v_mfma_f32_16x16x32_bf16 v[26:29], v[248:251], v[152:155], v[26:29]
	v_mfma_f32_16x16x32_bf16 v[22:25], v[184:187], v[160:163], v[22:25]
	v_mfma_f32_16x16x32_bf16 v[18:21], v[248:251], v[160:163], v[18:21]
	v_mfma_f32_16x16x32_bf16 v[14:17], v[184:187], v[168:171], v[14:17]
	v_mfma_f32_16x16x32_bf16 v[10:13], v[248:251], v[168:171], v[10:13]
	v_mfma_f32_16x16x32_bf16 v[6:9], v[184:187], v[176:179], v[6:9]
	v_mfma_f32_16x16x32_bf16 v[2:5], v[248:251], v[176:179], v[2:5]
	s_addk_i32 s70, 0x100
	s_mov_b64 s[46:47], 0x200
	v_lshl_add_u64 v[130:131], v[130:131], 0, s[46:47]
	s_cmp_ge_i32 s2, s59
	s_cbranch_scc1 .Lrot_exit
	s_andn2_b64 vcc, exec, s[30:31]
	s_cbranch_vccz .Lrot_seam
	s_barrier
	s_branch .LBB0_254
.Lrot_exit:
	s_barrier
	s_branch .LBB0_262

.Lrot_seamchk:
	s_cmp_lt_i32 s2, 32
	s_cbranch_scc1 .LBB0_258
	s_cmp_eq_u32 s2, 32
	s_cselect_b64 s[46:47], -1, 0
	s_cbranch_execz .LBB0_259
	s_branch .LBB0_260
